# per-segment s_setprio toggles removed; one static s_setprio 1 for waves 4-7 at kernel entry
# speedup vs baseline: 1.0016x; 1.0016x over previous
.LBB0_1:
	s_add_u32 s2, s0, 0xe0
	s_addc_u32 s3, s1, 0
	v_writelane_b32 v253, s2, 3
	s_load_dwordx2 s[4:5], s[0:1], 0xd0
	s_load_dwordx4 s[8:11], s[0:1], 0xc0
	v_writelane_b32 v253, s3, 4
	s_load_dword s90, s[0:1], 0xe0
	s_load_dwordx2 s[2:3], s[0:1], 0xd8
	v_and_b32_e32 v228, 0x3ff, v0
	v_and_b32_e32 v0, 0x3fffffff, v0
	v_mbcnt_lo_u32_b32 v2, -1, 0
	v_mov_b32_e32 v1, 0
	s_waitcnt lgkmcnt(0)
	s_add_i32 s3, s2, 1
	v_writelane_b32 v253, s3, 5
	v_writelane_b32 v253, s8, 6
	s_add_u32 s6, s4, 0x1f95a500
	s_addc_u32 s7, s5, 0
	v_writelane_b32 v253, s9, 7
	v_writelane_b32 v253, s10, 8
	v_writelane_b32 v253, s11, 9
	v_writelane_b32 v253, s6, 10
	s_load_dwordx16 s[8:23], s[0:1], 0x0
	v_mov_b32_e32 v229, 1
	v_writelane_b32 v253, s7, 11
	s_add_u32 s6, s4, 0x1f95aa00
	s_addc_u32 s7, s5, 0
	v_writelane_b32 v253, s6, 12
	s_movk_i32 s91, 0x8f
	s_movk_i32 s87, 0x90
	v_writelane_b32 v253, s7, 13
	s_add_u32 s6, s4, 0x1f95a980
	s_addc_u32 s7, s5, 0
	v_writelane_b32 v253, s6, 14
	s_mov_b32 s88, 0xfffffc0
	s_movk_i32 s89, 0x6000
	v_writelane_b32 v253, s7, 15
	s_add_u32 s6, s4, 0x1f95a580
	s_addc_u32 s7, s5, 0
	v_writelane_b32 v253, s6, 16
	s_movk_i32 s86, 0x84
	s_mov_b32 s65, 0x12000
	v_writelane_b32 v253, s7, 17
	s_add_u32 s6, s4, 0x1f95a600
	s_addc_u32 s7, s5, 0
	v_writelane_b32 v253, s6, 18
	s_mov_b32 s94, 0xbfb8aa3b
	v_mov_b32_e32 v230, 0x358637bd
	v_writelane_b32 v253, s7, 19
	s_add_u32 s6, s4, 0x1f95a680
	s_addc_u32 s7, s5, 0
	v_writelane_b32 v253, s6, 20
	s_mov_b32 s95, 0x800000
	v_mov_b32_e32 v210, 0x3f4ccccd
	v_writelane_b32 v253, s7, 21
	s_add_u32 s6, s4, 0x1f95a700
	s_addc_u32 s7, s5, 0
	v_writelane_b32 v253, s6, 22
	v_mbcnt_hi_u32_b32 v231, -1, v2
	v_mov_b32_e32 v232, 0x41b17218
	v_writelane_b32 v253, s7, 23
	s_add_u32 s6, s4, 0x1f95a780
	s_addc_u32 s7, s5, 0
	v_writelane_b32 v253, s6, 24
	v_mov_b32_e32 v233, 0x13c00000
	v_mov_b32_e32 v234, 0x10600000
	v_writelane_b32 v253, s7, 25
	s_add_u32 s6, s4, 0x1f95a800
	s_addc_u32 s7, s5, 0
	v_writelane_b32 v253, s6, 26
	v_mov_b32_e32 v235, 0xfffff800
	v_mov_b32_e32 v236, 0xfffffb00
	v_writelane_b32 v253, s7, 27
	s_add_u32 s6, s4, 0x1f95a880
	v_writelane_b32 v253, s4, 28
	s_addc_u32 s7, s5, 0
	s_add_i32 s3, 0, 0x12100
	v_writelane_b32 v253, s5, 29
	v_writelane_b32 v253, s6, 30
	s_mov_b32 s4, s2
	s_add_i32 s33, 0, 0x257f0
	v_writelane_b32 v253, s7, 31
	v_writelane_b32 v253, s3, 32
	v_cmp_eq_u32_e64 s[2:3], 0, v0
	v_mov_b32_e32 v237, 0x200
	v_mov_b32_e32 v238, 0x100
	v_writelane_b32 v253, s2, 33
	v_mov_b32_e32 v242, 0x1a0
	v_mov_b32_e32 v244, 11
	v_writelane_b32 v253, s3, 34
	s_waitcnt lgkmcnt(0)
	v_writelane_b32 v253, s8, 35
	s_movk_i32 s82, 0x2000
	s_mov_b32 s83, 0x3f317217
	v_writelane_b32 v253, s9, 36
	v_writelane_b32 v253, s10, 37
	v_writelane_b32 v253, s11, 38
	v_writelane_b32 v253, s12, 39
	v_writelane_b32 v253, s13, 40
	v_writelane_b32 v253, s14, 41
	v_writelane_b32 v253, s15, 42
	v_writelane_b32 v253, s16, 43
	v_writelane_b32 v253, s17, 44
	v_writelane_b32 v253, s18, 45
	v_writelane_b32 v253, s19, 46
	v_writelane_b32 v253, s20, 47
	v_writelane_b32 v253, s21, 48
	v_writelane_b32 v253, s22, 49
	v_writelane_b32 v253, s23, 50
	s_load_dwordx16 s[8:23], s[0:1], 0x40
	s_mov_b32 s80, 0x7f800000
	s_movk_i32 s81, 0x4000
	s_movk_i32 s92, 0x6880
	s_mov_b32 s39, 0
	s_waitcnt lgkmcnt(0)
	v_writelane_b32 v253, s8, 51
	s_mov_b64 s[42:43], 0x20000
	s_mov_b64 s[96:97], 0x40000
	v_writelane_b32 v253, s9, 52
	v_writelane_b32 v253, s10, 53
	v_writelane_b32 v253, s11, 54
	v_writelane_b32 v253, s12, 55
	v_writelane_b32 v253, s13, 56
	v_writelane_b32 v253, s14, 57
	v_writelane_b32 v253, s15, 58
	v_writelane_b32 v253, s16, 59
	v_writelane_b32 v253, s17, 60
	v_writelane_b32 v253, s18, 61
	v_writelane_b32 v254, s21, 0
	v_writelane_b32 v253, s19, 62
	v_writelane_b32 v254, s22, 1
	v_writelane_b32 v253, s20, 63
	v_writelane_b32 v254, s23, 2
	s_load_dwordx16 s[8:23], s[0:1], 0x80
	s_mov_b64 s[76:77], 0x60000
	s_mov_b64 s[84:85], 0x30000
	s_waitcnt lgkmcnt(0)
	v_writelane_b32 v254, s8, 3
	s_nop 1
	v_writelane_b32 v254, s9, 4
	v_writelane_b32 v254, s10, 5
	v_writelane_b32 v254, s11, 6
	v_writelane_b32 v254, s12, 7
	v_writelane_b32 v254, s13, 8
	v_writelane_b32 v254, s14, 9
	v_writelane_b32 v254, s15, 10
	v_writelane_b32 v254, s16, 11
	v_writelane_b32 v254, s17, 12
	v_writelane_b32 v254, s18, 13
	v_writelane_b32 v254, s19, 14
	v_writelane_b32 v254, s20, 15
	v_writelane_b32 v254, s21, 16
	v_writelane_b32 v254, s22, 17
	v_writelane_b32 v254, s23, 18
	v_writelane_b32 v254, s90, 19
	v_readfirstlane_b32 s0, v228
	s_nop 3
	s_lshr_b32 s0, s0, 8
	s_cmp_eq_u32 s0, 1
	s_cbranch_scc0 .Lstatic_prio_skip
	s_setprio 1
.Lstatic_prio_skip:
	s_branch .LBB0_4
.LBB0_2:
	s_or_b64 exec, exec, s[0:1]

.LBB0_56:
	s_bitcmp1_b32 s19, 0
	s_cselect_b32 s20, 0xd800, 0
	s_add_i32 s20, s20, 0
	v_add_u32_e32 v90, s20, v139
	v_add_u32_e32 v140, v90, v138
	v_add_u32_e32 v90, s20, v137
	v_add_u32_e32 v141, v90, v138
	ds_read_b128 v[106:109], v140
	ds_read_b128 v[94:97], v140 offset:32
	ds_read_b128 v[110:113], v140 offset:4608
	ds_read_b128 v[90:93], v140 offset:4640
	ds_read_b128 v[114:117], v141 offset:36864
	ds_read_b128 v[98:101], v141 offset:36896
	ds_read_b128 v[118:121], v141 offset:41472
	ds_read_b128 v[102:105], v141 offset:41504
	s_add_i32 s20, s19, 1
	s_cmp_ge_i32 s20, s18
	s_waitcnt lgkmcnt(3)
	v_mfma_f32_32x32x16_bf16 v[50:65], v[114:117], v[106:109], v[50:65]
	s_waitcnt lgkmcnt(1)
	v_mfma_f32_32x32x16_bf16 v[34:49], v[118:121], v[106:109], v[34:49]
	v_mfma_f32_32x32x16_bf16 v[18:33], v[114:117], v[110:113], v[18:33]
	v_mfma_f32_32x32x16_bf16 v[2:17], v[118:121], v[110:113], v[2:17]
	ds_read_b128 v[114:117], v140 offset:64
	ds_read_b128 v[106:109], v140 offset:4672
	ds_read_b128 v[118:121], v141 offset:36928
	ds_read_b128 v[110:113], v141 offset:41536
	s_cbranch_scc1 .LBB0_58
	s_bitcmp1_b32 s20, 0
	s_cselect_b32 s21, 0xd800, 0
	v_add3_u32 v142, v136, s21, v135
	s_waitcnt vmcnt(5)
	ds_write_b128 v142, v[66:69]
	s_waitcnt vmcnt(4)
	ds_write_b128 v142, v[70:73] offset:9216
	s_waitcnt vmcnt(3)
	ds_write_b128 v142, v[74:77] offset:18432
	s_waitcnt vmcnt(2)
	ds_write_b128 v142, v[78:81] offset:27648
	s_waitcnt vmcnt(1)
	ds_write_b128 v142, v[82:85] offset:36864
	s_waitcnt vmcnt(0)
	ds_write_b128 v142, v[86:89] offset:46080

.LBB0_60:
	v_mfma_f32_32x32x16_bf16 v[50:65], v[98:101], v[94:97], v[50:65]
	s_waitcnt lgkmcnt(4)
	v_mfma_f32_32x32x16_bf16 v[34:49], v[102:105], v[94:97], v[34:49]
	v_mfma_f32_32x32x16_bf16 v[18:33], v[98:101], v[90:93], v[18:33]
	v_mfma_f32_32x32x16_bf16 v[2:17], v[102:105], v[90:93], v[2:17]
	ds_read_b128 v[90:93], v140 offset:96
	ds_read_b128 v[94:97], v140 offset:4704
	ds_read_b128 v[98:101], v141 offset:36960
	ds_read_b128 v[102:105], v141 offset:41568
	s_waitcnt lgkmcnt(5)
	v_mfma_f32_32x32x16_bf16 v[50:65], v[118:121], v[114:117], v[50:65]
	s_waitcnt lgkmcnt(4)
	v_mfma_f32_32x32x16_bf16 v[34:49], v[110:113], v[114:117], v[34:49]
	v_mfma_f32_32x32x16_bf16 v[18:33], v[118:121], v[106:109], v[18:33]
	v_mfma_f32_32x32x16_bf16 v[2:17], v[110:113], v[106:109], v[2:17]
	s_waitcnt lgkmcnt(1)
	v_mfma_f32_32x32x16_bf16 v[50:65], v[98:101], v[90:93], v[50:65]
	s_waitcnt lgkmcnt(0)
	v_mfma_f32_32x32x16_bf16 v[34:49], v[102:105], v[90:93], v[34:49]
	v_mfma_f32_32x32x16_bf16 v[18:33], v[98:101], v[94:97], v[18:33]
	v_mfma_f32_32x32x16_bf16 v[2:17], v[102:105], v[94:97], v[2:17]
	s_waitcnt lgkmcnt(0)
	s_barrier
	s_cmp_lg_u32 s18, s20
	v_add_u32_e32 v0, 64, v0
	s_cbranch_scc0 .LBB0_47
	s_mov_b32 s19, s20
	s_branch .LBB0_56

.LBB0_87:
	s_bitcmp1_b32 s9, 0
	s_cselect_b32 s21, 0x12000, 0
	s_add_i32 s21, s21, 0
	v_add_u32_e32 v162, s21, v247
	v_add_u32_e32 v250, v162, v248
	v_add_u32_e32 v162, s21, v248
	v_add_u32_e32 v243, v162, v249
	ds_read_b128 v[170:173], v250
	ds_read_b128 v[166:169], v250 offset:32
	ds_read_b128 v[190:193], v250 offset:4608
	ds_read_b128 v[162:165], v250 offset:4640
	ds_read_b128 v[194:197], v243 offset:36864
	ds_read_b128 v[174:177], v243 offset:36896
	ds_read_b128 v[198:201], v243 offset:41472
	ds_read_b128 v[178:181], v243 offset:41504
	ds_read_b128 v[202:205], v243 offset:46080
	ds_read_b128 v[182:185], v243 offset:46112
	ds_read_b128 v[206:209], v243 offset:50688
	ds_read_b128 v[186:189], v243 offset:50720
	s_add_i32 s21, s9, 1
	s_cmp_ge_i32 s21, s7
	s_waitcnt lgkmcnt(7)
	v_mfma_f32_32x32x16_bf16 v[114:129], v[194:197], v[170:173], v[114:129]
	s_waitcnt lgkmcnt(5)
	v_mfma_f32_32x32x16_bf16 v[98:113], v[198:201], v[170:173], v[98:113]
	s_waitcnt lgkmcnt(3)
	v_mfma_f32_32x32x16_bf16 v[82:97], v[202:205], v[170:173], v[82:97]
	s_waitcnt lgkmcnt(1)
	v_mfma_f32_32x32x16_bf16 v[66:81], v[206:209], v[170:173], v[66:81]
	v_mfma_f32_32x32x16_bf16 v[50:65], v[194:197], v[190:193], v[50:65]
	v_mfma_f32_32x32x16_bf16 v[34:49], v[198:201], v[190:193], v[34:49]
	v_mfma_f32_32x32x16_bf16 v[18:33], v[202:205], v[190:193], v[18:33]
	v_mfma_f32_32x32x16_bf16 v[2:17], v[206:209], v[190:193], v[2:17]
	ds_read_b128 v[202:205], v250 offset:64
	ds_read_b128 v[170:173], v250 offset:4672
	ds_read_b128 v[206:209], v243 offset:36928
	ds_read_b128 v[198:201], v243 offset:41536
	ds_read_b128 v[194:197], v243 offset:46144
	ds_read_b128 v[190:193], v243 offset:50752
	s_cbranch_scc1 .LBB0_89
	s_bitcmp1_b32 s21, 0
	s_cselect_b32 s22, 0x12000, 0
	v_add3_u32 v239, v246, s22, v245
	s_waitcnt vmcnt(7)
	ds_write_b128 v239, v[130:133]
	s_waitcnt vmcnt(6)
	ds_write_b128 v239, v[134:137] offset:9216
	s_waitcnt vmcnt(5)
	ds_write_b128 v239, v[138:141] offset:18432
	s_waitcnt vmcnt(4)
	ds_write_b128 v239, v[142:145] offset:27648
	s_waitcnt vmcnt(3)
	ds_write_b128 v239, v[146:149] offset:36864
	s_waitcnt vmcnt(2)
	ds_write_b128 v239, v[150:153] offset:46080
	s_waitcnt vmcnt(1)
	ds_write_b128 v239, v[154:157] offset:55296
	s_waitcnt vmcnt(0)
	ds_write_b128 v239, v[158:161] offset:64512

.LBB0_91:
	v_mfma_f32_32x32x16_bf16 v[114:129], v[174:177], v[166:169], v[114:129]
	v_mfma_f32_32x32x16_bf16 v[98:113], v[178:181], v[166:169], v[98:113]
	v_mfma_f32_32x32x16_bf16 v[82:97], v[182:185], v[166:169], v[82:97]
	s_waitcnt lgkmcnt(6)
	v_mfma_f32_32x32x16_bf16 v[66:81], v[186:189], v[166:169], v[66:81]
	v_mfma_f32_32x32x16_bf16 v[50:65], v[174:177], v[162:165], v[50:65]
	v_mfma_f32_32x32x16_bf16 v[34:49], v[178:181], v[162:165], v[34:49]
	v_mfma_f32_32x32x16_bf16 v[18:33], v[182:185], v[162:165], v[18:33]
	v_mfma_f32_32x32x16_bf16 v[2:17], v[186:189], v[162:165], v[2:17]
	ds_read_b128 v[162:165], v250 offset:96
	ds_read_b128 v[166:169], v250 offset:4704
	ds_read_b128 v[174:177], v243 offset:36960
	ds_read_b128 v[178:181], v243 offset:41568
	ds_read_b128 v[182:185], v243 offset:46176
	ds_read_b128 v[186:189], v243 offset:50784
	s_waitcnt lgkmcnt(9)
	v_mfma_f32_32x32x16_bf16 v[114:129], v[206:209], v[202:205], v[114:129]
	s_waitcnt lgkmcnt(8)
	v_mfma_f32_32x32x16_bf16 v[98:113], v[198:201], v[202:205], v[98:113]
	s_waitcnt lgkmcnt(7)
	v_mfma_f32_32x32x16_bf16 v[82:97], v[194:197], v[202:205], v[82:97]
	s_waitcnt lgkmcnt(6)
	v_mfma_f32_32x32x16_bf16 v[66:81], v[190:193], v[202:205], v[66:81]
	v_mfma_f32_32x32x16_bf16 v[50:65], v[206:209], v[170:173], v[50:65]
	v_mfma_f32_32x32x16_bf16 v[34:49], v[198:201], v[170:173], v[34:49]
	v_mfma_f32_32x32x16_bf16 v[18:33], v[194:197], v[170:173], v[18:33]
	v_mfma_f32_32x32x16_bf16 v[2:17], v[190:193], v[170:173], v[2:17]
	s_waitcnt lgkmcnt(3)
	v_mfma_f32_32x32x16_bf16 v[114:129], v[174:177], v[162:165], v[114:129]
	s_waitcnt lgkmcnt(2)
	v_mfma_f32_32x32x16_bf16 v[98:113], v[178:181], v[162:165], v[98:113]
	s_waitcnt lgkmcnt(1)
	v_mfma_f32_32x32x16_bf16 v[82:97], v[182:185], v[162:165], v[82:97]
	s_waitcnt lgkmcnt(0)
	v_mfma_f32_32x32x16_bf16 v[66:81], v[186:189], v[162:165], v[66:81]
	v_mfma_f32_32x32x16_bf16 v[50:65], v[174:177], v[166:169], v[50:65]
	v_mfma_f32_32x32x16_bf16 v[34:49], v[178:181], v[166:169], v[34:49]
	v_mfma_f32_32x32x16_bf16 v[18:33], v[182:185], v[166:169], v[18:33]
	v_mfma_f32_32x32x16_bf16 v[2:17], v[186:189], v[166:169], v[2:17]
	s_waitcnt lgkmcnt(0)
	s_barrier
	s_cmp_lg_u32 s7, s21
	v_add_u32_e32 v0, 64, v0
	s_cbranch_scc0 .LBB0_78
	s_mov_b32 s9, s21
	s_branch .LBB0_87

.LBB0_117:
	s_bitcmp1_b32 s21, 0
	s_cselect_b32 s22, 0xd800, 0
	s_add_i32 s22, s22, 0
	v_add_u32_e32 v90, s22, v139
	v_add_u32_e32 v140, v90, v138
	v_add_u32_e32 v90, s22, v137
	v_add_u32_e32 v141, v90, v138
	ds_read_b128 v[106:109], v140
	ds_read_b128 v[94:97], v140 offset:32
	ds_read_b128 v[110:113], v140 offset:4608
	ds_read_b128 v[90:93], v140 offset:4640
	ds_read_b128 v[114:117], v141 offset:36864
	ds_read_b128 v[98:101], v141 offset:36896
	ds_read_b128 v[118:121], v141 offset:41472
	ds_read_b128 v[102:105], v141 offset:41504
	s_add_i32 s22, s21, 1
	s_cmp_ge_i32 s22, s7
	s_waitcnt lgkmcnt(3)
	v_mfma_f32_32x32x16_bf16 v[50:65], v[114:117], v[106:109], v[50:65]
	s_waitcnt lgkmcnt(1)
	v_mfma_f32_32x32x16_bf16 v[34:49], v[118:121], v[106:109], v[34:49]
	v_mfma_f32_32x32x16_bf16 v[18:33], v[114:117], v[110:113], v[18:33]
	v_mfma_f32_32x32x16_bf16 v[2:17], v[118:121], v[110:113], v[2:17]
	ds_read_b128 v[114:117], v140 offset:64
	ds_read_b128 v[106:109], v140 offset:4672
	ds_read_b128 v[118:121], v141 offset:36928
	ds_read_b128 v[110:113], v141 offset:41536
	s_cbranch_scc1 .LBB0_119
	s_bitcmp1_b32 s22, 0
	s_cselect_b32 s23, 0xd800, 0
	v_add3_u32 v142, v136, s23, v135
	s_waitcnt vmcnt(5)
	ds_write_b128 v142, v[66:69]
	s_waitcnt vmcnt(4)
	ds_write_b128 v142, v[70:73] offset:9216
	s_waitcnt vmcnt(3)
	ds_write_b128 v142, v[74:77] offset:18432
	s_waitcnt vmcnt(2)
	ds_write_b128 v142, v[78:81] offset:27648
	s_waitcnt vmcnt(1)
	ds_write_b128 v142, v[82:85] offset:36864
	s_waitcnt vmcnt(0)
	ds_write_b128 v142, v[86:89] offset:46080

.LBB0_121:
	v_mfma_f32_32x32x16_bf16 v[50:65], v[98:101], v[94:97], v[50:65]
	s_waitcnt lgkmcnt(4)
	v_mfma_f32_32x32x16_bf16 v[34:49], v[102:105], v[94:97], v[34:49]
	v_mfma_f32_32x32x16_bf16 v[18:33], v[98:101], v[90:93], v[18:33]
	v_mfma_f32_32x32x16_bf16 v[2:17], v[102:105], v[90:93], v[2:17]
	ds_read_b128 v[90:93], v140 offset:96
	ds_read_b128 v[94:97], v140 offset:4704
	ds_read_b128 v[98:101], v141 offset:36960
	ds_read_b128 v[102:105], v141 offset:41568
	s_waitcnt lgkmcnt(5)
	v_mfma_f32_32x32x16_bf16 v[50:65], v[118:121], v[114:117], v[50:65]
	s_waitcnt lgkmcnt(4)
	v_mfma_f32_32x32x16_bf16 v[34:49], v[110:113], v[114:117], v[34:49]
	v_mfma_f32_32x32x16_bf16 v[18:33], v[118:121], v[106:109], v[18:33]
	v_mfma_f32_32x32x16_bf16 v[2:17], v[110:113], v[106:109], v[2:17]
	s_waitcnt lgkmcnt(1)
	v_mfma_f32_32x32x16_bf16 v[50:65], v[98:101], v[90:93], v[50:65]
	s_waitcnt lgkmcnt(0)
	v_mfma_f32_32x32x16_bf16 v[34:49], v[102:105], v[90:93], v[34:49]
	v_mfma_f32_32x32x16_bf16 v[18:33], v[98:101], v[94:97], v[18:33]
	v_mfma_f32_32x32x16_bf16 v[2:17], v[102:105], v[94:97], v[2:17]
	s_waitcnt lgkmcnt(0)
	s_barrier
	s_cmp_lg_u32 s7, s22
	v_add_u32_e32 v0, 64, v0
	s_cbranch_scc0 .LBB0_108
	s_mov_b32 s21, s22
	s_branch .LBB0_117

.LBB0_140:
	s_bitcmp1_b32 s11, 0
	s_cselect_b32 s28, 0xd800, 0
	s_add_i32 s28, s28, 0
	v_add_u32_e32 v26, s28, v154
	v_add_u32_e32 v155, v26, v153
	v_add_u32_e32 v26, s28, v152
	v_add_u32_e32 v156, v26, v153
	ds_read_b128 v[42:45], v155
	ds_read_b128 v[30:33], v155 offset:32
	ds_read_b128 v[46:49], v155 offset:4608
	ds_read_b128 v[26:29], v155 offset:4640
	ds_read_b128 v[50:53], v156 offset:36864
	ds_read_b128 v[34:37], v156 offset:36896
	ds_read_b128 v[54:57], v156 offset:41472
	ds_read_b128 v[38:41], v156 offset:41504
	s_add_i32 s28, s11, 1
	s_cmp_ge_i32 s28, s10
	s_waitcnt lgkmcnt(3)
	v_mfma_f32_32x32x16_bf16 v[114:129], v[50:53], v[42:45], v[114:129]
	s_waitcnt lgkmcnt(1)
	v_mfma_f32_32x32x16_bf16 v[98:113], v[54:57], v[42:45], v[98:113]
	v_mfma_f32_32x32x16_bf16 v[82:97], v[50:53], v[46:49], v[82:97]
	v_mfma_f32_32x32x16_bf16 v[66:81], v[54:57], v[46:49], v[66:81]
	ds_read_b128 v[50:53], v155 offset:64
	ds_read_b128 v[42:45], v155 offset:4672
	ds_read_b128 v[54:57], v156 offset:36928
	ds_read_b128 v[46:49], v156 offset:41536
	s_cbranch_scc1 .LBB0_142
	s_bitcmp1_b32 s28, 0
	s_cselect_b32 s29, 0xd800, 0
	v_add3_u32 v157, v151, s29, v150
	s_waitcnt vmcnt(5)
	ds_write_b128 v157, v[2:5]
	s_waitcnt vmcnt(4)
	ds_write_b128 v157, v[6:9] offset:9216
	s_waitcnt vmcnt(3)
	ds_write_b128 v157, v[10:13] offset:18432
	s_waitcnt vmcnt(2)
	ds_write_b128 v157, v[14:17] offset:27648
	s_waitcnt vmcnt(1)
	ds_write_b128 v157, v[18:21] offset:36864
	s_waitcnt vmcnt(0)
	ds_write_b128 v157, v[22:25] offset:46080

.LBB0_144:
	v_mfma_f32_32x32x16_bf16 v[114:129], v[34:37], v[30:33], v[114:129]
	s_waitcnt lgkmcnt(4)
	v_mfma_f32_32x32x16_bf16 v[98:113], v[38:41], v[30:33], v[98:113]
	v_mfma_f32_32x32x16_bf16 v[82:97], v[34:37], v[26:29], v[82:97]
	v_mfma_f32_32x32x16_bf16 v[66:81], v[38:41], v[26:29], v[66:81]
	ds_read_b128 v[26:29], v155 offset:96
	ds_read_b128 v[30:33], v155 offset:4704
	ds_read_b128 v[34:37], v156 offset:36960
	ds_read_b128 v[38:41], v156 offset:41568
	s_waitcnt lgkmcnt(5)
	v_mfma_f32_32x32x16_bf16 v[114:129], v[54:57], v[50:53], v[114:129]
	s_waitcnt lgkmcnt(4)
	v_mfma_f32_32x32x16_bf16 v[98:113], v[46:49], v[50:53], v[98:113]
	v_mfma_f32_32x32x16_bf16 v[82:97], v[54:57], v[42:45], v[82:97]
	v_mfma_f32_32x32x16_bf16 v[66:81], v[46:49], v[42:45], v[66:81]
	s_waitcnt lgkmcnt(1)
	v_mfma_f32_32x32x16_bf16 v[114:129], v[34:37], v[26:29], v[114:129]
	s_waitcnt lgkmcnt(0)
	v_mfma_f32_32x32x16_bf16 v[98:113], v[38:41], v[26:29], v[98:113]
	v_mfma_f32_32x32x16_bf16 v[82:97], v[34:37], v[30:33], v[82:97]
	v_mfma_f32_32x32x16_bf16 v[66:81], v[38:41], v[30:33], v[66:81]
	s_waitcnt lgkmcnt(0)
	s_barrier
	s_cmp_lg_u32 s10, s28
	v_add_u32_e32 v0, 64, v0
	s_cbranch_scc0 .LBB0_147
	s_mov_b32 s11, s28
	s_branch .LBB0_140

.LBB0_151:
	s_bitcmp1_b32 s29, 0
	s_cselect_b32 s30, 0xd800, 0
	s_add_i32 s30, s30, 0
	v_add_u32_e32 v170, s30, v243
	v_add_u32_e32 v239, v170, v252
	v_add_u32_e32 v170, s30, v251
	v_add_u32_e32 v240, v170, v252
	ds_read_b128 v[186:189], v239
	ds_read_b128 v[174:177], v239 offset:32
	ds_read_b128 v[190:193], v239 offset:4608
	ds_read_b128 v[170:173], v239 offset:4640
	ds_read_b128 v[194:197], v240 offset:36864
	ds_read_b128 v[178:181], v240 offset:36896
	ds_read_b128 v[198:201], v240 offset:41472
	ds_read_b128 v[182:185], v240 offset:41504
	s_add_i32 s30, s29, 1
	s_cmp_ge_i32 s30, s28
	s_waitcnt lgkmcnt(3)
	v_mfma_f32_32x32x16_bf16 v[50:65], v[194:197], v[186:189], v[50:65]
	s_waitcnt lgkmcnt(1)
	v_mfma_f32_32x32x16_bf16 v[34:49], v[198:201], v[186:189], v[34:49]
	v_mfma_f32_32x32x16_bf16 v[18:33], v[194:197], v[190:193], v[18:33]
	v_mfma_f32_32x32x16_bf16 v[2:17], v[198:201], v[190:193], v[2:17]
	ds_read_b128 v[194:197], v239 offset:64
	ds_read_b128 v[186:189], v239 offset:4672
	ds_read_b128 v[198:201], v240 offset:36928
	ds_read_b128 v[190:193], v240 offset:41536
	s_cbranch_scc1 .LBB0_153
	s_bitcmp1_b32 s30, 0
	s_cselect_b32 s31, 0xd800, 0
	v_add3_u32 v241, v250, s31, v249
	s_waitcnt vmcnt(5)
	ds_write_b128 v241, v[146:149]
	s_waitcnt vmcnt(4)
	ds_write_b128 v241, v[150:153] offset:9216
	s_waitcnt vmcnt(3)
	ds_write_b128 v241, v[154:157] offset:18432
	s_waitcnt vmcnt(2)
	ds_write_b128 v241, v[158:161] offset:27648
	s_waitcnt vmcnt(1)
	ds_write_b128 v241, v[162:165] offset:36864
	s_waitcnt vmcnt(0)
	ds_write_b128 v241, v[166:169] offset:46080

.LBB0_155:
	v_mfma_f32_32x32x16_bf16 v[50:65], v[178:181], v[174:177], v[50:65]
	s_waitcnt lgkmcnt(4)
	v_mfma_f32_32x32x16_bf16 v[34:49], v[182:185], v[174:177], v[34:49]
	v_mfma_f32_32x32x16_bf16 v[18:33], v[178:181], v[170:173], v[18:33]
	v_mfma_f32_32x32x16_bf16 v[2:17], v[182:185], v[170:173], v[2:17]
	ds_read_b128 v[170:173], v239 offset:96
	ds_read_b128 v[174:177], v239 offset:4704
	ds_read_b128 v[178:181], v240 offset:36960
	ds_read_b128 v[182:185], v240 offset:41568
	s_waitcnt lgkmcnt(5)
	v_mfma_f32_32x32x16_bf16 v[50:65], v[198:201], v[194:197], v[50:65]
	s_waitcnt lgkmcnt(4)
	v_mfma_f32_32x32x16_bf16 v[34:49], v[190:193], v[194:197], v[34:49]
	v_mfma_f32_32x32x16_bf16 v[18:33], v[198:201], v[186:189], v[18:33]
	v_mfma_f32_32x32x16_bf16 v[2:17], v[190:193], v[186:189], v[2:17]
	s_waitcnt lgkmcnt(1)
	v_mfma_f32_32x32x16_bf16 v[50:65], v[178:181], v[170:173], v[50:65]
	s_waitcnt lgkmcnt(0)
	v_mfma_f32_32x32x16_bf16 v[34:49], v[182:185], v[170:173], v[34:49]
	v_mfma_f32_32x32x16_bf16 v[18:33], v[178:181], v[174:177], v[18:33]
	v_mfma_f32_32x32x16_bf16 v[2:17], v[182:185], v[174:177], v[2:17]
	s_waitcnt lgkmcnt(0)
	s_barrier
	s_cmp_lg_u32 s28, s30
	v_add_u32_e32 v0, 64, v0
	s_cbranch_scc0 .LBB0_135
	s_mov_b32 s29, s30
	s_branch .LBB0_151

.LBB0_266:
	s_bitcmp1_b32 s9, 0
	s_cselect_b32 s10, 0xd800, 0
	s_add_i32 s10, s10, 0
	v_add_u32_e32 v90, s10, v138
	v_add_u32_e32 v139, v90, v137
	v_add_u32_e32 v90, s10, v136
	v_add_u32_e32 v140, v90, v137
	ds_read_b128 v[106:109], v139
	ds_read_b128 v[94:97], v139 offset:32
	ds_read_b128 v[110:113], v139 offset:4608
	ds_read_b128 v[90:93], v139 offset:4640
	ds_read_b128 v[114:117], v140 offset:36864
	ds_read_b128 v[98:101], v140 offset:36896
	ds_read_b128 v[118:121], v140 offset:41472
	ds_read_b128 v[102:105], v140 offset:41504
	s_add_i32 s10, s9, 1
	s_cmp_ge_i32 s10, s8
	s_waitcnt lgkmcnt(3)
	v_mfma_f32_32x32x16_bf16 v[50:65], v[114:117], v[106:109], v[50:65]
	s_waitcnt lgkmcnt(1)
	v_mfma_f32_32x32x16_bf16 v[34:49], v[118:121], v[106:109], v[34:49]
	v_mfma_f32_32x32x16_bf16 v[18:33], v[114:117], v[110:113], v[18:33]
	v_mfma_f32_32x32x16_bf16 v[2:17], v[118:121], v[110:113], v[2:17]
	ds_read_b128 v[114:117], v139 offset:64
	ds_read_b128 v[106:109], v139 offset:4672
	ds_read_b128 v[118:121], v140 offset:36928
	ds_read_b128 v[110:113], v140 offset:41536
	s_cbranch_scc1 .LBB0_268
	s_bitcmp1_b32 s10, 0
	s_cselect_b32 s11, 0xd800, 0
	v_add3_u32 v141, v135, s11, v134
	s_waitcnt vmcnt(5)
	ds_write_b128 v141, v[66:69]
	s_waitcnt vmcnt(4)
	ds_write_b128 v141, v[70:73] offset:9216
	s_waitcnt vmcnt(3)
	ds_write_b128 v141, v[74:77] offset:18432
	s_waitcnt vmcnt(2)
	ds_write_b128 v141, v[78:81] offset:27648
	s_waitcnt vmcnt(1)
	ds_write_b128 v141, v[82:85] offset:36864
	s_waitcnt vmcnt(0)
	ds_write_b128 v141, v[86:89] offset:46080

.LBB0_270:
	v_mfma_f32_32x32x16_bf16 v[50:65], v[98:101], v[94:97], v[50:65]
	s_waitcnt lgkmcnt(4)
	v_mfma_f32_32x32x16_bf16 v[34:49], v[102:105], v[94:97], v[34:49]
	v_mfma_f32_32x32x16_bf16 v[18:33], v[98:101], v[90:93], v[18:33]
	v_mfma_f32_32x32x16_bf16 v[2:17], v[102:105], v[90:93], v[2:17]
	ds_read_b128 v[90:93], v139 offset:96
	ds_read_b128 v[94:97], v139 offset:4704
	ds_read_b128 v[98:101], v140 offset:36960
	ds_read_b128 v[102:105], v140 offset:41568
	s_waitcnt lgkmcnt(5)
	v_mfma_f32_32x32x16_bf16 v[50:65], v[118:121], v[114:117], v[50:65]
	s_waitcnt lgkmcnt(4)
	v_mfma_f32_32x32x16_bf16 v[34:49], v[110:113], v[114:117], v[34:49]
	v_mfma_f32_32x32x16_bf16 v[18:33], v[118:121], v[106:109], v[18:33]
	v_mfma_f32_32x32x16_bf16 v[2:17], v[110:113], v[106:109], v[2:17]
	s_waitcnt lgkmcnt(1)
	v_mfma_f32_32x32x16_bf16 v[50:65], v[98:101], v[90:93], v[50:65]
	s_waitcnt lgkmcnt(0)
	v_mfma_f32_32x32x16_bf16 v[34:49], v[102:105], v[90:93], v[34:49]
	v_mfma_f32_32x32x16_bf16 v[18:33], v[98:101], v[94:97], v[18:33]
	v_mfma_f32_32x32x16_bf16 v[2:17], v[102:105], v[94:97], v[2:17]
	s_waitcnt lgkmcnt(0)
	s_barrier
	s_cmp_lg_u32 s8, s10
	v_add_u32_e32 v0, 64, v0
	s_cbranch_scc0 .LBB0_273
	s_mov_b32 s9, s10
	s_branch .LBB0_266

.LBB0_277:
	s_bitcmp1_b32 s5, 0
	s_cselect_b32 s8, 0xd800, 0
	s_add_i32 s8, s8, 0
	v_add_u32_e32 v154, s8, v204
	v_add_u32_e32 v205, v154, v203
	v_add_u32_e32 v154, s8, v202
	v_add_u32_e32 v206, v154, v203
	ds_read_b128 v[170:173], v205
	ds_read_b128 v[158:161], v205 offset:32
	ds_read_b128 v[174:177], v205 offset:4608
	ds_read_b128 v[154:157], v205 offset:4640
	ds_read_b128 v[178:181], v206 offset:36864
	ds_read_b128 v[162:165], v206 offset:36896
	ds_read_b128 v[182:185], v206 offset:41472
	ds_read_b128 v[166:169], v206 offset:41504
	s_add_i32 s8, s5, 1
	s_cmp_ge_i32 s8, s4
	s_waitcnt lgkmcnt(3)
	v_mfma_f32_32x32x16_bf16 v[114:129], v[178:181], v[170:173], v[114:129]
	s_waitcnt lgkmcnt(1)
	v_mfma_f32_32x32x16_bf16 v[98:113], v[182:185], v[170:173], v[98:113]
	v_mfma_f32_32x32x16_bf16 v[82:97], v[178:181], v[174:177], v[82:97]
	v_mfma_f32_32x32x16_bf16 v[66:81], v[182:185], v[174:177], v[66:81]
	ds_read_b128 v[178:181], v205 offset:64
	ds_read_b128 v[170:173], v205 offset:4672
	ds_read_b128 v[182:185], v206 offset:36928
	ds_read_b128 v[174:177], v206 offset:41536
	s_cbranch_scc1 .LBB0_279
	s_bitcmp1_b32 s8, 0
	s_cselect_b32 s9, 0xd800, 0
	v_add3_u32 v207, v201, s9, v200
	s_waitcnt vmcnt(5)
	ds_write_b128 v207, v[130:133]
	s_waitcnt vmcnt(4)
	ds_write_b128 v207, v[134:137] offset:9216
	s_waitcnt vmcnt(3)
	ds_write_b128 v207, v[138:141] offset:18432
	s_waitcnt vmcnt(2)
	ds_write_b128 v207, v[142:145] offset:27648
	s_waitcnt vmcnt(1)
	ds_write_b128 v207, v[146:149] offset:36864
	s_waitcnt vmcnt(0)
	ds_write_b128 v207, v[150:153] offset:46080

.LBB0_281:
	v_mfma_f32_32x32x16_bf16 v[114:129], v[162:165], v[158:161], v[114:129]
	s_waitcnt lgkmcnt(4)
	v_mfma_f32_32x32x16_bf16 v[98:113], v[166:169], v[158:161], v[98:113]
	v_mfma_f32_32x32x16_bf16 v[82:97], v[162:165], v[154:157], v[82:97]
	v_mfma_f32_32x32x16_bf16 v[66:81], v[166:169], v[154:157], v[66:81]
	ds_read_b128 v[154:157], v205 offset:96
	ds_read_b128 v[158:161], v205 offset:4704
	ds_read_b128 v[162:165], v206 offset:36960
	ds_read_b128 v[166:169], v206 offset:41568
	s_waitcnt lgkmcnt(5)
	v_mfma_f32_32x32x16_bf16 v[114:129], v[182:185], v[178:181], v[114:129]
	s_waitcnt lgkmcnt(4)
	v_mfma_f32_32x32x16_bf16 v[98:113], v[174:177], v[178:181], v[98:113]
	v_mfma_f32_32x32x16_bf16 v[82:97], v[182:185], v[170:173], v[82:97]
	v_mfma_f32_32x32x16_bf16 v[66:81], v[174:177], v[170:173], v[66:81]
	s_waitcnt lgkmcnt(1)
	v_mfma_f32_32x32x16_bf16 v[114:129], v[162:165], v[154:157], v[114:129]
	s_waitcnt lgkmcnt(0)
	v_mfma_f32_32x32x16_bf16 v[98:113], v[166:169], v[154:157], v[98:113]
	v_mfma_f32_32x32x16_bf16 v[82:97], v[162:165], v[158:161], v[82:97]
	v_mfma_f32_32x32x16_bf16 v[66:81], v[166:169], v[158:161], v[66:81]
	s_waitcnt lgkmcnt(0)
	s_barrier
	s_cmp_lg_u32 s4, s8
	v_add_u32_e32 v0, 64, v0
	s_cbranch_scc0 .LBB0_284
	s_mov_b32 s5, s8
	s_branch .LBB0_277

.LBB0_349:
	s_bitcmp1_b32 s2, 0
	s_cselect_b32 s3, 0x12000, 0
	s_add_i32 s3, s3, 0
	v_add_u32_e32 v162, s3, v247
	v_add_u32_e32 v250, v162, v248
	v_add_u32_e32 v162, s3, v248
	v_add_u32_e32 v243, v162, v249
	ds_read_b128 v[170:173], v250
	ds_read_b128 v[166:169], v250 offset:32
	ds_read_b128 v[190:193], v250 offset:4608
	ds_read_b128 v[162:165], v250 offset:4640
	ds_read_b128 v[194:197], v243 offset:36864
	ds_read_b128 v[174:177], v243 offset:36896
	ds_read_b128 v[198:201], v243 offset:41472
	ds_read_b128 v[178:181], v243 offset:41504
	ds_read_b128 v[202:205], v243 offset:46080
	ds_read_b128 v[182:185], v243 offset:46112
	ds_read_b128 v[206:209], v243 offset:50688
	ds_read_b128 v[186:189], v243 offset:50720
	s_add_i32 s3, s2, 1
	s_cmp_ge_i32 s3, s1
	s_waitcnt lgkmcnt(7)
	v_mfma_f32_32x32x16_bf16 v[114:129], v[194:197], v[170:173], v[114:129]
	s_waitcnt lgkmcnt(5)
	v_mfma_f32_32x32x16_bf16 v[98:113], v[198:201], v[170:173], v[98:113]
	s_waitcnt lgkmcnt(3)
	v_mfma_f32_32x32x16_bf16 v[50:65], v[202:205], v[170:173], v[50:65]
	s_waitcnt lgkmcnt(1)
	v_mfma_f32_32x32x16_bf16 v[34:49], v[206:209], v[170:173], v[34:49]
	v_mfma_f32_32x32x16_bf16 v[82:97], v[194:197], v[190:193], v[82:97]
	v_mfma_f32_32x32x16_bf16 v[66:81], v[198:201], v[190:193], v[66:81]
	v_mfma_f32_32x32x16_bf16 v[18:33], v[202:205], v[190:193], v[18:33]
	v_mfma_f32_32x32x16_bf16 v[2:17], v[206:209], v[190:193], v[2:17]
	ds_read_b128 v[202:205], v250 offset:64
	ds_read_b128 v[170:173], v250 offset:4672
	ds_read_b128 v[206:209], v243 offset:36928
	ds_read_b128 v[198:201], v243 offset:41536
	ds_read_b128 v[194:197], v243 offset:46144
	ds_read_b128 v[190:193], v243 offset:50752
	s_cbranch_scc1 .LBB0_351
	s_bitcmp1_b32 s3, 0
	s_cselect_b32 s5, 0x12000, 0
	v_add3_u32 v239, v246, s5, v245
	s_waitcnt vmcnt(7)
	ds_write_b128 v239, v[130:133]
	s_waitcnt vmcnt(6)
	ds_write_b128 v239, v[134:137] offset:9216
	s_waitcnt vmcnt(5)
	ds_write_b128 v239, v[138:141] offset:18432
	s_waitcnt vmcnt(4)
	ds_write_b128 v239, v[142:145] offset:27648
	s_waitcnt vmcnt(3)
	ds_write_b128 v239, v[146:149] offset:36864
	s_waitcnt vmcnt(2)
	ds_write_b128 v239, v[150:153] offset:46080
	s_waitcnt vmcnt(1)
	ds_write_b128 v239, v[154:157] offset:55296
	s_waitcnt vmcnt(0)
	ds_write_b128 v239, v[158:161] offset:64512

.LBB0_353:
	v_mfma_f32_32x32x16_bf16 v[114:129], v[174:177], v[166:169], v[114:129]
	v_mfma_f32_32x32x16_bf16 v[98:113], v[178:181], v[166:169], v[98:113]
	v_mfma_f32_32x32x16_bf16 v[50:65], v[182:185], v[166:169], v[50:65]
	s_waitcnt lgkmcnt(6)
	v_mfma_f32_32x32x16_bf16 v[34:49], v[186:189], v[166:169], v[34:49]
	v_mfma_f32_32x32x16_bf16 v[82:97], v[174:177], v[162:165], v[82:97]
	v_mfma_f32_32x32x16_bf16 v[66:81], v[178:181], v[162:165], v[66:81]
	v_mfma_f32_32x32x16_bf16 v[18:33], v[182:185], v[162:165], v[18:33]
	v_mfma_f32_32x32x16_bf16 v[2:17], v[186:189], v[162:165], v[2:17]
	ds_read_b128 v[162:165], v250 offset:96
	ds_read_b128 v[166:169], v250 offset:4704
	ds_read_b128 v[174:177], v243 offset:36960
	ds_read_b128 v[178:181], v243 offset:41568
	ds_read_b128 v[182:185], v243 offset:46176
	ds_read_b128 v[186:189], v243 offset:50784
	s_waitcnt lgkmcnt(9)
	v_mfma_f32_32x32x16_bf16 v[114:129], v[206:209], v[202:205], v[114:129]
	s_waitcnt lgkmcnt(8)
	v_mfma_f32_32x32x16_bf16 v[98:113], v[198:201], v[202:205], v[98:113]
	s_waitcnt lgkmcnt(7)
	v_mfma_f32_32x32x16_bf16 v[50:65], v[194:197], v[202:205], v[50:65]
	s_waitcnt lgkmcnt(6)
	v_mfma_f32_32x32x16_bf16 v[34:49], v[190:193], v[202:205], v[34:49]
	v_mfma_f32_32x32x16_bf16 v[82:97], v[206:209], v[170:173], v[82:97]
	v_mfma_f32_32x32x16_bf16 v[66:81], v[198:201], v[170:173], v[66:81]
	v_mfma_f32_32x32x16_bf16 v[18:33], v[194:197], v[170:173], v[18:33]
	v_mfma_f32_32x32x16_bf16 v[2:17], v[190:193], v[170:173], v[2:17]
	s_waitcnt lgkmcnt(3)
	v_mfma_f32_32x32x16_bf16 v[114:129], v[174:177], v[162:165], v[114:129]
	s_waitcnt lgkmcnt(2)
	v_mfma_f32_32x32x16_bf16 v[98:113], v[178:181], v[162:165], v[98:113]
	s_waitcnt lgkmcnt(1)
	v_mfma_f32_32x32x16_bf16 v[50:65], v[182:185], v[162:165], v[50:65]
	s_waitcnt lgkmcnt(0)
	v_mfma_f32_32x32x16_bf16 v[34:49], v[186:189], v[162:165], v[34:49]
	v_mfma_f32_32x32x16_bf16 v[82:97], v[174:177], v[166:169], v[82:97]
	v_mfma_f32_32x32x16_bf16 v[66:81], v[178:181], v[166:169], v[66:81]
	v_mfma_f32_32x32x16_bf16 v[18:33], v[182:185], v[166:169], v[18:33]
	v_mfma_f32_32x32x16_bf16 v[2:17], v[186:189], v[166:169], v[2:17]
	s_waitcnt lgkmcnt(0)
	s_barrier
	s_cmp_lg_u32 s1, s3
	v_add_u32_e32 v0, 64, v0
	s_cbranch_scc0 .LBB0_356
	s_mov_b32 s2, s3
	s_branch .LBB0_349
